# colperm: plain in-proj tiles with permuted GEMM columns (wave owns 64 contiguous P columns) and DPP-merged stores writing full 128-byte lines (8 rows x 128 B per instruction); on top of v90
# speedup vs baseline: 1.0146x; 1.0009x over previous
; #define LAS __attribute__((address_space(3)))
; __device__ __forceinline__ unsigned cvt_pk_bf16(float lo, float hi) { unsigned r; asm volatile("v_cvt_pk_bf16_f32 %0, %1, %2" : "=v"(r) : "v"(lo), "v"(hi)); return r; }
; template <bool MAPIN>
; __device__ __forceinline__ void transpose_item(const float* W, int K, int N, bf16_t* WT, LAS float* scr, int item, int lane, const float* gk = nullptr) {
;     ...
;     for (int j = 0; j < 4; ++j) { const int n = (lane >> 3) + 8 * j; const LAS float* s = scr + (8 * c) * 33 + n;
;         f32x4 ga = (f32x4){1.f, 1.f, 1.f, 1.f}, gb = ga;
;         if (gk) { ga = *(const f32x4*)(gk + k0 + 8 * c); gb = *(const f32x4*)(gk + k0 + 8 * c + 4); }
;         u32x4 o; o.x = cvt_pk_bf16(s[0 * 33] * ga[0], s[1 * 33] * ga[1]); o.y = cvt_pk_bf16(s[2 * 33] * ga[2], s[3 * 33] * ga[3]); o.z = cvt_pk_bf16(s[4 * 33] * gb[0], s[5 * 33] * gb[1]); o.w = cvt_pk_bf16(s[6 * 33] * gb[2], s[7 * 33] * gb[3]);
;         const int nd = MAPIN ? win_map(n0 + n) : (n0 + n);
;         *(u32x4*)(WT + (size_t)nd * K + k0 + 8 * c) = o; }
.Ltw_go:
	s_cmp_eq_u32 s25, 0
	s_cbranch_scc0 .Ltw_noperm
	s_cmpk_lt_u32 s24, 0x1200
	s_cbranch_scc0 .Ltw_noperm
	s_and_b32 s26, s24, 0xff
	s_bfe_u32 s27, s26, 0x10005
	s_lshl_b32 s27, s27, 7
	s_lshr_b32 s26, s26, 6
	s_lshl_b32 s26, s26, 5
	s_andn2_b32 s24, s24, 0xff
	s_add_u32 s24, s24, s27
	s_add_u32 s24, s24, s26

; #define GAS __attribute__((address_space(1)))
;     __device__ __forceinline__ void operator()(const f32x4 (&acc)[2][2][4][2], const Unit& u, int wr, int wc, int fr, int fq, const PG8_LAS float* tab) const {
;         const int pn = u.pn; const bool is_rope = (pn < 4) || (pn == 8); const bool is_z = (pn >= 18); const float qs = (pn < 4) ? 0.125f : 1.0f;
; #pragma unroll
;         for (int ai = 0; ai < 2; ++ai)
; #pragma unroll
;             for (int m = 0; m < 4; ++m) {
;                 const int row = u.pm * BM + ai * HALF + wr * 64 + m * 16 + fr;
;                 const float rs = rsqrtf(tab[ai * HALF + wr * 64 + m * 16 + fr] * (1.0f / 2048.0f) + 1e-6f);
;                 const int pos = row < 16384 ? (row & 8191) : (row - 16384);
;                 GAS bf16_t* rowp = (GAS bf16_t*)P + (size_t)row * 5120;
;                 if (is_z) {
;                     const f32x4 z0 = (acc[ai][0][m][0] * rs) * (acc[ai][1][m][0] * rs), z1 = (acc[ai][0][m][1] * rs) * (acc[ai][1][m][1] * rs);
;                     u32x4 w; w.x = cvt_pk_bf16(z0[0], z0[1]); w.y = cvt_pk_bf16(z0[2], z0[3]); w.z = cvt_pk_bf16(z1[0], z1[1]); w.w = cvt_pk_bf16(z1[2], z1[3]);
;                     *(GAS u32x4*)(rowp + 4608 + (pn - 18) * 128 + wc * 32 + 8 * fq) = w;
;                     continue;
;                 }
; #pragma unroll
;                 for (int bj = 0; bj < 2; ++bj) {
;                     const int col0 = pn * BM + bj * HALF + wc * 32 + 8 * fq;
;                     f32x4 v0 = acc[ai][bj][m][0] * rs, v1 = acc[ai][bj][m][1] * rs;
;                     if (is_rope) {
;                         const GAS f32x4* rp = (const GAS f32x4*)((const GAS f32x2*)rope + (size_t)pos * 32 + ((col0 & 63) >> 1));
;                         const f32x4 cs0 = rp[0], cs1 = rp[1];
;                         f32x4 o0, o1;
;                         o0[0] = v0[0] * cs0[0] - v0[1] * cs0[1]; o0[1] = v0[1] * cs0[0] + v0[0] * cs0[1];
;                         o0[2] = v0[2] * cs0[2] - v0[3] * cs0[3]; o0[3] = v0[3] * cs0[2] + v0[2] * cs0[3];
;                         o1[0] = v1[0] * cs1[0] - v1[1] * cs1[1]; o1[1] = v1[1] * cs1[0] + v1[0] * cs1[1];
;                         o1[2] = v1[2] * cs1[2] - v1[3] * cs1[3]; o1[3] = v1[3] * cs1[2] + v1[2] * cs1[3];
;                         v0 = o0 * qs; v1 = o1 * qs;
;                     }
;                     {
.Lei_plain_test:
	s_cmp_gt_i32 s0, 17
	s_cbranch_scc1 .Lei_zmark
	s_and_b32 s4, s3, 1
	s_lshl_b32 s4, s4, 10
	v_add_u32_e32 v171, s4, v172
	ds_read_b32 v154, v171 offset:0
	ds_read_b32 v156, v171 offset:64
	ds_read_b32 v158, v171 offset:128
	ds_read_b32 v160, v171 offset:192
	ds_read_b32 v155, v171 offset:512
	ds_read_b32 v157, v171 offset:576
	ds_read_b32 v159, v171 offset:640
	ds_read_b32 v161, v171 offset:704
	s_mul_i32 s4, s1, 0x280000
	s_lshl_b32 s5, s0, 9
	s_add_u32 s4, s4, s5
	s_add_u32 s6, s86, s4
	s_addc_u32 s7, s87, 0
	v_bfe_u32 v232, v1, 3, 1
	v_and_b32_e32 v233, 31, v173
	v_lshlrev_b32_e32 v233, 1, v233
	v_lshrrev_b32_e32 v230, 5, v173
	v_lshl_add_u32 v233, v230, 7, v233
	v_lshl_add_u32 v233, v232, 6, v233
	v_mul_u32_u24_e32 v230, 0x2800, v1
	v_add_u32_e32 v230, v230, v233
	v_mul_u32_u24_e32 v233, 0x14000, v232
	v_sub_u32_e32 v230, v230, v233
	v_add_u32_e32 v231, 0x14000, v230
	s_waitcnt lgkmcnt(0)
	v_fmamk_f32 v154, v154, 0x3a000000, v236
	v_fmamk_f32 v156, v156, 0x3a000000, v236
	v_fmamk_f32 v158, v158, 0x3a000000, v236
	v_fmamk_f32 v160, v160, 0x3a000000, v236
	v_fmamk_f32 v155, v155, 0x3a000000, v236
	v_fmamk_f32 v157, v157, 0x3a000000, v236
	v_fmamk_f32 v159, v159, 0x3a000000, v236
	v_fmamk_f32 v161, v161, 0x3a000000, v236
	v_rsq_f32_e32 v154, v154
	v_rsq_f32_e32 v156, v156
	v_rsq_f32_e32 v158, v158
	v_rsq_f32_e32 v160, v160
	v_rsq_f32_e32 v155, v155
	v_rsq_f32_e32 v157, v157
	v_rsq_f32_e32 v159, v159
	v_rsq_f32_e32 v161, v161
	v_pk_mul_f32 v[126:127], v[126:127], v[154:155] op_sel_hi:[1,0]
	v_pk_mul_f32 v[128:129], v[128:129], v[154:155] op_sel_hi:[1,0]
	v_pk_mul_f32 v[122:123], v[122:123], v[154:155] op_sel_hi:[1,0]
	v_pk_mul_f32 v[124:125], v[124:125], v[154:155] op_sel_hi:[1,0]
	v_cvt_pk_bf16_f32 v126, v126, v127
	v_cvt_pk_bf16_f32 v127, v128, v129
	v_cvt_pk_bf16_f32 v128, v122, v123
	v_cvt_pk_bf16_f32 v129, v124, v125
	v_pk_mul_f32 v[118:119], v[118:119], v[154:155] op_sel_hi:[1,0]
	v_pk_mul_f32 v[120:121], v[120:121], v[154:155] op_sel_hi:[1,0]
	v_pk_mul_f32 v[114:115], v[114:115], v[154:155] op_sel_hi:[1,0]
	v_pk_mul_f32 v[116:117], v[116:117], v[154:155] op_sel_hi:[1,0]
	v_cvt_pk_bf16_f32 v118, v118, v119
	v_cvt_pk_bf16_f32 v119, v120, v121
	v_cvt_pk_bf16_f32 v120, v114, v115
	v_cvt_pk_bf16_f32 v121, v116, v117
	v_mov_b32_e32 v166, v126
	v_mov_b32_e32 v167, v127
	v_mov_b32_e32 v168, v128
	v_mov_b32_e32 v169, v129
	v_mov_b32_dpp v126, v118 row_ror:8 row_mask:0xf bank_mask:0xc
	v_mov_b32_dpp v127, v119 row_ror:8 row_mask:0xf bank_mask:0xc
	v_mov_b32_dpp v128, v120 row_ror:8 row_mask:0xf bank_mask:0xc
	v_mov_b32_dpp v129, v121 row_ror:8 row_mask:0xf bank_mask:0xc
	v_mov_b32_dpp v118, v166 row_ror:8 row_mask:0xf bank_mask:0x3
	v_mov_b32_dpp v119, v167 row_ror:8 row_mask:0xf bank_mask:0x3
	v_mov_b32_dpp v120, v168 row_ror:8 row_mask:0xf bank_mask:0x3
	v_mov_b32_dpp v121, v169 row_ror:8 row_mask:0xf bank_mask:0x3
	s_mov_b64 s[10:11], s[6:7]
	global_store_dwordx4 v230, v[126:129], s[10:11]
	global_store_dwordx4 v231, v[118:121], s[10:11]
	v_pk_mul_f32 v[110:111], v[110:111], v[156:157] op_sel_hi:[1,0]
	v_pk_mul_f32 v[112:113], v[112:113], v[156:157] op_sel_hi:[1,0]
	v_pk_mul_f32 v[106:107], v[106:107], v[156:157] op_sel_hi:[1,0]
	v_pk_mul_f32 v[108:109], v[108:109], v[156:157] op_sel_hi:[1,0]
	v_cvt_pk_bf16_f32 v110, v110, v111
	v_cvt_pk_bf16_f32 v111, v112, v113
	v_cvt_pk_bf16_f32 v112, v106, v107
	v_cvt_pk_bf16_f32 v113, v108, v109
	v_pk_mul_f32 v[102:103], v[102:103], v[156:157] op_sel_hi:[1,0]
	v_pk_mul_f32 v[104:105], v[104:105], v[156:157] op_sel_hi:[1,0]
	v_pk_mul_f32 v[98:99], v[98:99], v[156:157] op_sel_hi:[1,0]
	v_pk_mul_f32 v[100:101], v[100:101], v[156:157] op_sel_hi:[1,0]
	v_cvt_pk_bf16_f32 v102, v102, v103
	v_cvt_pk_bf16_f32 v103, v104, v105
	v_cvt_pk_bf16_f32 v104, v98, v99
	v_cvt_pk_bf16_f32 v105, v100, v101
	v_mov_b32_e32 v166, v110
	v_mov_b32_e32 v167, v111
	v_mov_b32_e32 v168, v112
	v_mov_b32_e32 v169, v113
	v_mov_b32_dpp v110, v102 row_ror:8 row_mask:0xf bank_mask:0xc
	v_mov_b32_dpp v111, v103 row_ror:8 row_mask:0xf bank_mask:0xc
	v_mov_b32_dpp v112, v104 row_ror:8 row_mask:0xf bank_mask:0xc
	v_mov_b32_dpp v113, v105 row_ror:8 row_mask:0xf bank_mask:0xc
	v_mov_b32_dpp v102, v166 row_ror:8 row_mask:0xf bank_mask:0x3
	v_mov_b32_dpp v103, v167 row_ror:8 row_mask:0xf bank_mask:0x3
	v_mov_b32_dpp v104, v168 row_ror:8 row_mask:0xf bank_mask:0x3
	v_mov_b32_dpp v105, v169 row_ror:8 row_mask:0xf bank_mask:0x3
	s_add_u32 s10, s6, 0x28000
	s_addc_u32 s11, s7, 0
	global_store_dwordx4 v230, v[110:113], s[10:11]
	global_store_dwordx4 v231, v[102:105], s[10:11]
	v_pk_mul_f32 v[94:95], v[94:95], v[158:159] op_sel_hi:[1,0]
	v_pk_mul_f32 v[96:97], v[96:97], v[158:159] op_sel_hi:[1,0]
	v_pk_mul_f32 v[90:91], v[90:91], v[158:159] op_sel_hi:[1,0]
	v_pk_mul_f32 v[92:93], v[92:93], v[158:159] op_sel_hi:[1,0]
	v_cvt_pk_bf16_f32 v94, v94, v95
	v_cvt_pk_bf16_f32 v95, v96, v97
	v_cvt_pk_bf16_f32 v96, v90, v91
	v_cvt_pk_bf16_f32 v97, v92, v93
	v_pk_mul_f32 v[86:87], v[86:87], v[158:159] op_sel_hi:[1,0]
	v_pk_mul_f32 v[88:89], v[88:89], v[158:159] op_sel_hi:[1,0]
	v_pk_mul_f32 v[82:83], v[82:83], v[158:159] op_sel_hi:[1,0]
	v_pk_mul_f32 v[84:85], v[84:85], v[158:159] op_sel_hi:[1,0]
	v_cvt_pk_bf16_f32 v86, v86, v87
	v_cvt_pk_bf16_f32 v87, v88, v89
	v_cvt_pk_bf16_f32 v88, v82, v83
	v_cvt_pk_bf16_f32 v89, v84, v85
	v_mov_b32_e32 v166, v94
	v_mov_b32_e32 v167, v95
	v_mov_b32_e32 v168, v96
	v_mov_b32_e32 v169, v97
	v_mov_b32_dpp v94, v86 row_ror:8 row_mask:0xf bank_mask:0xc
	v_mov_b32_dpp v95, v87 row_ror:8 row_mask:0xf bank_mask:0xc
	v_mov_b32_dpp v96, v88 row_ror:8 row_mask:0xf bank_mask:0xc
	v_mov_b32_dpp v97, v89 row_ror:8 row_mask:0xf bank_mask:0xc
; #define GAS __attribute__((address_space(1)))
;     __device__ __forceinline__ void operator()(const f32x4 (&acc)[2][2][4][2], const Unit& u, int wr, int wc, int fr, int fq, const PG8_LAS float* tab) const {
;         const int pn = u.pn; const bool is_rope = (pn < 4) || (pn == 8); const bool is_z = (pn >= 18); const float qs = (pn < 4) ? 0.125f : 1.0f;
; #pragma unroll
;         for (int ai = 0; ai < 2; ++ai)
; #pragma unroll
;             for (int m = 0; m < 4; ++m) {
;                 const int row = u.pm * BM + ai * HALF + wr * 64 + m * 16 + fr;
;                 const float rs = rsqrtf(tab[ai * HALF + wr * 64 + m * 16 + fr] * (1.0f / 2048.0f) + 1e-6f);
;                 const int pos = row < 16384 ? (row & 8191) : (row - 16384);
;                 GAS bf16_t* rowp = (GAS bf16_t*)P + (size_t)row * 5120;
;                 if (is_z) {
;                     const f32x4 z0 = (acc[ai][0][m][0] * rs) * (acc[ai][1][m][0] * rs), z1 = (acc[ai][0][m][1] * rs) * (acc[ai][1][m][1] * rs);
;                     u32x4 w; w.x = cvt_pk_bf16(z0[0], z0[1]); w.y = cvt_pk_bf16(z0[2], z0[3]); w.z = cvt_pk_bf16(z1[0], z1[1]); w.w = cvt_pk_bf16(z1[2], z1[3]);
;                     *(GAS u32x4*)(rowp + 4608 + (pn - 18) * 128 + wc * 32 + 8 * fq) = w;
;                     continue;
;                 }
; #pragma unroll
;                 for (int bj = 0; bj < 2; ++bj) {
;                     const int col0 = pn * BM + bj * HALF + wc * 32 + 8 * fq;
;                     f32x4 v0 = acc[ai][bj][m][0] * rs, v1 = acc[ai][bj][m][1] * rs;
;                     if (is_rope) {
;                         const GAS f32x4* rp = (const GAS f32x4*)((const GAS f32x2*)rope + (size_t)pos * 32 + ((col0 & 63) >> 1));
;                         const f32x4 cs0 = rp[0], cs1 = rp[1];
;                         f32x4 o0, o1;
;                         o0[0] = v0[0] * cs0[0] - v0[1] * cs0[1]; o0[1] = v0[1] * cs0[0] + v0[0] * cs0[1];
;                         o0[2] = v0[2] * cs0[2] - v0[3] * cs0[3]; o0[3] = v0[3] * cs0[2] + v0[2] * cs0[3];
;                         o1[0] = v1[0] * cs1[0] - v1[1] * cs1[1]; o1[1] = v1[1] * cs1[0] + v1[0] * cs1[1];
;                         o1[2] = v1[2] * cs1[2] - v1[3] * cs1[3]; o1[3] = v1[3] * cs1[2] + v1[2] * cs1[3];
;                         v0 = o0 * qs; v1 = o1 * qs;
;                     }
;                     {
	v_mov_b32_dpp v86, v166 row_ror:8 row_mask:0xf bank_mask:0x3
	v_mov_b32_dpp v87, v167 row_ror:8 row_mask:0xf bank_mask:0x3
	v_mov_b32_dpp v88, v168 row_ror:8 row_mask:0xf bank_mask:0x3
	v_mov_b32_dpp v89, v169 row_ror:8 row_mask:0xf bank_mask:0x3
	s_add_u32 s10, s6, 0x50000
	s_addc_u32 s11, s7, 0
	global_store_dwordx4 v230, v[94:97], s[10:11]
	global_store_dwordx4 v231, v[86:89], s[10:11]
	v_pk_mul_f32 v[78:79], v[78:79], v[160:161] op_sel_hi:[1,0]
	v_pk_mul_f32 v[80:81], v[80:81], v[160:161] op_sel_hi:[1,0]
	v_pk_mul_f32 v[74:75], v[74:75], v[160:161] op_sel_hi:[1,0]
	v_pk_mul_f32 v[76:77], v[76:77], v[160:161] op_sel_hi:[1,0]
	v_cvt_pk_bf16_f32 v78, v78, v79
	v_cvt_pk_bf16_f32 v79, v80, v81
	v_cvt_pk_bf16_f32 v80, v74, v75
	v_cvt_pk_bf16_f32 v81, v76, v77
	v_pk_mul_f32 v[70:71], v[70:71], v[160:161] op_sel_hi:[1,0]
	v_pk_mul_f32 v[72:73], v[72:73], v[160:161] op_sel_hi:[1,0]
	v_pk_mul_f32 v[66:67], v[66:67], v[160:161] op_sel_hi:[1,0]
	v_pk_mul_f32 v[68:69], v[68:69], v[160:161] op_sel_hi:[1,0]
	v_cvt_pk_bf16_f32 v70, v70, v71
	v_cvt_pk_bf16_f32 v71, v72, v73
	v_cvt_pk_bf16_f32 v72, v66, v67
	v_cvt_pk_bf16_f32 v73, v68, v69
	v_mov_b32_e32 v166, v78
	v_mov_b32_e32 v167, v79
	v_mov_b32_e32 v168, v80
	v_mov_b32_e32 v169, v81
	v_mov_b32_dpp v78, v70 row_ror:8 row_mask:0xf bank_mask:0xc
	v_mov_b32_dpp v79, v71 row_ror:8 row_mask:0xf bank_mask:0xc
	v_mov_b32_dpp v80, v72 row_ror:8 row_mask:0xf bank_mask:0xc
	v_mov_b32_dpp v81, v73 row_ror:8 row_mask:0xf bank_mask:0xc
	v_mov_b32_dpp v70, v166 row_ror:8 row_mask:0xf bank_mask:0x3
	v_mov_b32_dpp v71, v167 row_ror:8 row_mask:0xf bank_mask:0x3
	v_mov_b32_dpp v72, v168 row_ror:8 row_mask:0xf bank_mask:0x3
	v_mov_b32_dpp v73, v169 row_ror:8 row_mask:0xf bank_mask:0x3
	s_add_u32 s10, s6, 0x78000
	s_addc_u32 s11, s7, 0
	global_store_dwordx4 v230, v[78:81], s[10:11]
	global_store_dwordx4 v231, v[70:73], s[10:11]
	v_mov_b32_e32 v154, v155
	v_mov_b32_e32 v156, v157
	v_mov_b32_e32 v158, v159
	v_mov_b32_e32 v160, v161
	v_pk_mul_f32 v[62:63], v[62:63], v[154:155] op_sel_hi:[1,0]
	v_pk_mul_f32 v[64:65], v[64:65], v[154:155] op_sel_hi:[1,0]
	v_pk_mul_f32 v[58:59], v[58:59], v[154:155] op_sel_hi:[1,0]
	v_pk_mul_f32 v[60:61], v[60:61], v[154:155] op_sel_hi:[1,0]
	v_cvt_pk_bf16_f32 v62, v62, v63
	v_cvt_pk_bf16_f32 v63, v64, v65
	v_cvt_pk_bf16_f32 v64, v58, v59
	v_cvt_pk_bf16_f32 v65, v60, v61
	v_pk_mul_f32 v[54:55], v[54:55], v[154:155] op_sel_hi:[1,0]
	v_pk_mul_f32 v[56:57], v[56:57], v[154:155] op_sel_hi:[1,0]
	v_pk_mul_f32 v[50:51], v[50:51], v[154:155] op_sel_hi:[1,0]
	v_pk_mul_f32 v[52:53], v[52:53], v[154:155] op_sel_hi:[1,0]
	v_cvt_pk_bf16_f32 v54, v54, v55
	v_cvt_pk_bf16_f32 v55, v56, v57
	v_cvt_pk_bf16_f32 v56, v50, v51
	v_cvt_pk_bf16_f32 v57, v52, v53
	v_mov_b32_e32 v166, v62
	v_mov_b32_e32 v167, v63
	v_mov_b32_e32 v168, v64
	v_mov_b32_e32 v169, v65
	v_mov_b32_dpp v62, v54 row_ror:8 row_mask:0xf bank_mask:0xc
	v_mov_b32_dpp v63, v55 row_ror:8 row_mask:0xf bank_mask:0xc
	v_mov_b32_dpp v64, v56 row_ror:8 row_mask:0xf bank_mask:0xc
	v_mov_b32_dpp v65, v57 row_ror:8 row_mask:0xf bank_mask:0xc
	v_mov_b32_dpp v54, v166 row_ror:8 row_mask:0xf bank_mask:0x3
	v_mov_b32_dpp v55, v167 row_ror:8 row_mask:0xf bank_mask:0x3
	v_mov_b32_dpp v56, v168 row_ror:8 row_mask:0xf bank_mask:0x3
	v_mov_b32_dpp v57, v169 row_ror:8 row_mask:0xf bank_mask:0x3
	s_add_u32 s10, s6, 0x140000
	s_addc_u32 s11, s7, 0
	global_store_dwordx4 v230, v[62:65], s[10:11]
	global_store_dwordx4 v231, v[54:57], s[10:11]
	v_pk_mul_f32 v[46:47], v[46:47], v[156:157] op_sel_hi:[1,0]
	v_pk_mul_f32 v[48:49], v[48:49], v[156:157] op_sel_hi:[1,0]
	v_pk_mul_f32 v[42:43], v[42:43], v[156:157] op_sel_hi:[1,0]
	v_pk_mul_f32 v[44:45], v[44:45], v[156:157] op_sel_hi:[1,0]
	v_cvt_pk_bf16_f32 v46, v46, v47
	v_cvt_pk_bf16_f32 v47, v48, v49
	v_cvt_pk_bf16_f32 v48, v42, v43
	v_cvt_pk_bf16_f32 v49, v44, v45
	v_pk_mul_f32 v[38:39], v[38:39], v[156:157] op_sel_hi:[1,0]
	v_pk_mul_f32 v[40:41], v[40:41], v[156:157] op_sel_hi:[1,0]
; #define GAS __attribute__((address_space(1)))
;     __device__ __forceinline__ void operator()(const f32x4 (&acc)[2][2][4][2], const Unit& u, int wr, int wc, int fr, int fq, const PG8_LAS float* tab) const {
;         const int pn = u.pn; const bool is_rope = (pn < 4) || (pn == 8); const bool is_z = (pn >= 18); const float qs = (pn < 4) ? 0.125f : 1.0f;
; #pragma unroll
;         for (int ai = 0; ai < 2; ++ai)
; #pragma unroll
;             for (int m = 0; m < 4; ++m) {
;                 const int row = u.pm * BM + ai * HALF + wr * 64 + m * 16 + fr;
;                 const float rs = rsqrtf(tab[ai * HALF + wr * 64 + m * 16 + fr] * (1.0f / 2048.0f) + 1e-6f);
;                 const int pos = row < 16384 ? (row & 8191) : (row - 16384);
;                 GAS bf16_t* rowp = (GAS bf16_t*)P + (size_t)row * 5120;
;                 if (is_z) {
;                     const f32x4 z0 = (acc[ai][0][m][0] * rs) * (acc[ai][1][m][0] * rs), z1 = (acc[ai][0][m][1] * rs) * (acc[ai][1][m][1] * rs);
;                     u32x4 w; w.x = cvt_pk_bf16(z0[0], z0[1]); w.y = cvt_pk_bf16(z0[2], z0[3]); w.z = cvt_pk_bf16(z1[0], z1[1]); w.w = cvt_pk_bf16(z1[2], z1[3]);
;                     *(GAS u32x4*)(rowp + 4608 + (pn - 18) * 128 + wc * 32 + 8 * fq) = w;
;                     continue;
;                 }
; #pragma unroll
;                 for (int bj = 0; bj < 2; ++bj) {
;                     const int col0 = pn * BM + bj * HALF + wc * 32 + 8 * fq;
;                     f32x4 v0 = acc[ai][bj][m][0] * rs, v1 = acc[ai][bj][m][1] * rs;
;                     if (is_rope) {
;                         const GAS f32x4* rp = (const GAS f32x4*)((const GAS f32x2*)rope + (size_t)pos * 32 + ((col0 & 63) >> 1));
;                         const f32x4 cs0 = rp[0], cs1 = rp[1];
;                         f32x4 o0, o1;
;                         o0[0] = v0[0] * cs0[0] - v0[1] * cs0[1]; o0[1] = v0[1] * cs0[0] + v0[0] * cs0[1];
;                         o0[2] = v0[2] * cs0[2] - v0[3] * cs0[3]; o0[3] = v0[3] * cs0[2] + v0[2] * cs0[3];
;                         o1[0] = v1[0] * cs1[0] - v1[1] * cs1[1]; o1[1] = v1[1] * cs1[0] + v1[0] * cs1[1];
;                         o1[2] = v1[2] * cs1[2] - v1[3] * cs1[3]; o1[3] = v1[3] * cs1[2] + v1[2] * cs1[3];
;                         v0 = o0 * qs; v1 = o1 * qs;
;                     }
;                     {
	v_pk_mul_f32 v[34:35], v[34:35], v[156:157] op_sel_hi:[1,0]
	v_pk_mul_f32 v[36:37], v[36:37], v[156:157] op_sel_hi:[1,0]
	v_cvt_pk_bf16_f32 v38, v38, v39
	v_cvt_pk_bf16_f32 v39, v40, v41
	v_cvt_pk_bf16_f32 v40, v34, v35
	v_cvt_pk_bf16_f32 v41, v36, v37
	v_mov_b32_e32 v166, v46
	v_mov_b32_e32 v167, v47
	v_mov_b32_e32 v168, v48
	v_mov_b32_e32 v169, v49
	v_mov_b32_dpp v46, v38 row_ror:8 row_mask:0xf bank_mask:0xc
	v_mov_b32_dpp v47, v39 row_ror:8 row_mask:0xf bank_mask:0xc
	v_mov_b32_dpp v48, v40 row_ror:8 row_mask:0xf bank_mask:0xc
	v_mov_b32_dpp v49, v41 row_ror:8 row_mask:0xf bank_mask:0xc
	v_mov_b32_dpp v38, v166 row_ror:8 row_mask:0xf bank_mask:0x3
	v_mov_b32_dpp v39, v167 row_ror:8 row_mask:0xf bank_mask:0x3
	v_mov_b32_dpp v40, v168 row_ror:8 row_mask:0xf bank_mask:0x3
	v_mov_b32_dpp v41, v169 row_ror:8 row_mask:0xf bank_mask:0x3
	s_add_u32 s10, s6, 0x168000
	s_addc_u32 s11, s7, 0
	global_store_dwordx4 v230, v[46:49], s[10:11]
	global_store_dwordx4 v231, v[38:41], s[10:11]
	v_pk_mul_f32 v[30:31], v[30:31], v[158:159] op_sel_hi:[1,0]
	v_pk_mul_f32 v[32:33], v[32:33], v[158:159] op_sel_hi:[1,0]
	v_pk_mul_f32 v[26:27], v[26:27], v[158:159] op_sel_hi:[1,0]
	v_pk_mul_f32 v[28:29], v[28:29], v[158:159] op_sel_hi:[1,0]
	v_cvt_pk_bf16_f32 v30, v30, v31
	v_cvt_pk_bf16_f32 v31, v32, v33
	v_cvt_pk_bf16_f32 v32, v26, v27
	v_cvt_pk_bf16_f32 v33, v28, v29
	v_pk_mul_f32 v[22:23], v[22:23], v[158:159] op_sel_hi:[1,0]
	v_pk_mul_f32 v[24:25], v[24:25], v[158:159] op_sel_hi:[1,0]
	v_pk_mul_f32 v[18:19], v[18:19], v[158:159] op_sel_hi:[1,0]
	v_pk_mul_f32 v[20:21], v[20:21], v[158:159] op_sel_hi:[1,0]
	v_cvt_pk_bf16_f32 v22, v22, v23
	v_cvt_pk_bf16_f32 v23, v24, v25
	v_cvt_pk_bf16_f32 v24, v18, v19
	v_cvt_pk_bf16_f32 v25, v20, v21
	v_mov_b32_e32 v166, v30
	v_mov_b32_e32 v167, v31
	v_mov_b32_e32 v168, v32
	v_mov_b32_e32 v169, v33
	v_mov_b32_dpp v30, v22 row_ror:8 row_mask:0xf bank_mask:0xc
	v_mov_b32_dpp v31, v23 row_ror:8 row_mask:0xf bank_mask:0xc
	v_mov_b32_dpp v32, v24 row_ror:8 row_mask:0xf bank_mask:0xc
	v_mov_b32_dpp v33, v25 row_ror:8 row_mask:0xf bank_mask:0xc
	v_mov_b32_dpp v22, v166 row_ror:8 row_mask:0xf bank_mask:0x3
	v_mov_b32_dpp v23, v167 row_ror:8 row_mask:0xf bank_mask:0x3
	v_mov_b32_dpp v24, v168 row_ror:8 row_mask:0xf bank_mask:0x3
	v_mov_b32_dpp v25, v169 row_ror:8 row_mask:0xf bank_mask:0x3
	s_add_u32 s10, s6, 0x190000
	s_addc_u32 s11, s7, 0
	global_store_dwordx4 v230, v[30:33], s[10:11]
	global_store_dwordx4 v231, v[22:25], s[10:11]
	v_pk_mul_f32 v[14:15], v[14:15], v[160:161] op_sel_hi:[1,0]
	v_pk_mul_f32 v[16:17], v[16:17], v[160:161] op_sel_hi:[1,0]
	v_pk_mul_f32 v[10:11], v[10:11], v[160:161] op_sel_hi:[1,0]
	v_pk_mul_f32 v[12:13], v[12:13], v[160:161] op_sel_hi:[1,0]
	v_cvt_pk_bf16_f32 v14, v14, v15
	v_cvt_pk_bf16_f32 v15, v16, v17
	v_cvt_pk_bf16_f32 v16, v10, v11
	v_cvt_pk_bf16_f32 v17, v12, v13
	v_pk_mul_f32 v[6:7], v[6:7], v[160:161] op_sel_hi:[1,0]
	v_pk_mul_f32 v[8:9], v[8:9], v[160:161] op_sel_hi:[1,0]
	v_pk_mul_f32 v[2:3], v[2:3], v[160:161] op_sel_hi:[1,0]
	v_pk_mul_f32 v[4:5], v[4:5], v[160:161] op_sel_hi:[1,0]
	v_cvt_pk_bf16_f32 v6, v6, v7
	v_cvt_pk_bf16_f32 v7, v8, v9
	v_cvt_pk_bf16_f32 v8, v2, v3
	v_cvt_pk_bf16_f32 v9, v4, v5
	v_mov_b32_e32 v166, v14
	v_mov_b32_e32 v167, v15
	v_mov_b32_e32 v168, v16
	v_mov_b32_e32 v169, v17
	v_mov_b32_dpp v14, v6 row_ror:8 row_mask:0xf bank_mask:0xc
	v_mov_b32_dpp v15, v7 row_ror:8 row_mask:0xf bank_mask:0xc
	v_mov_b32_dpp v16, v8 row_ror:8 row_mask:0xf bank_mask:0xc
	v_mov_b32_dpp v17, v9 row_ror:8 row_mask:0xf bank_mask:0xc
	v_mov_b32_dpp v6, v166 row_ror:8 row_mask:0xf bank_mask:0x3
	v_mov_b32_dpp v7, v167 row_ror:8 row_mask:0xf bank_mask:0x3
	v_mov_b32_dpp v8, v168 row_ror:8 row_mask:0xf bank_mask:0x3
	v_mov_b32_dpp v9, v169 row_ror:8 row_mask:0xf bank_mask:0x3
	s_add_u32 s10, s6, 0x1b8000
	s_addc_u32 s11, s7, 0
	global_store_dwordx4 v230, v[14:17], s[10:11]
	global_store_dwordx4 v231, v[6:9], s[10:11]
	s_branch .LBB0_406
